# P3 co-schedule regrouped so that all 16 workgroups of one (batch, head) run attention in the same time slot (one K/V working set per XCD L2 at a time)
# baseline (speedup 1.0000x reference)
.LBB0_965:
	v_readlane_b32 s0, v255, 15
	v_readlane_b32 s1, v255, 16
	s_or_b64 exec, exec, s[0:1]
	v_readlane_b32 s89, v255, 13
	v_readlane_b32 s72, v255, 10
	s_cmpk_lg_i32 s89, 0x100
	v_readlane_b32 s88, v255, 14
	v_readlane_b32 s73, v255, 11
	s_waitcnt lgkmcnt(0)
	s_barrier
	s_cbranch_scc1 .LBB0_1155
	v_readlane_b32 s1, v255, 12
	s_lshr_b32 s0, s1, 3
	s_and_b32 s78, s0, 2
	s_ashr_i32 s0, s88, 31
	s_lshr_b32 s0, s0, 29
	s_add_i32 s0, s88, s0
	s_ashr_i32 s85, s0, 3
	s_lshl_b32 s0, s88, 5
	s_mulk_i32 s85, 0xff01
	s_bfe_u32 s52, s1, 0x20003
	s_add_i32 s53, s85, s0
	s_cmp_eq_u32 s78, 0
	s_mov_b32 s7, 0
	s_cbranch_scc1 .LBB0_1049
	s_cmp_eq_u32 s52, 2
	s_cselect_b64 s[8:9], -1, 0
	s_ashr_i32 s79, s53, 4
	s_lshr_b32 s0, s79, 29
	s_add_i32 s1, s79, s0
	s_ashr_i32 s0, s1, 3
	s_and_b32 s1, s1, -8
	s_sub_i32 s6, s79, s1
	s_lshl_b32 s2, s6, 6
	s_and_b32 s12, s85, 15
	s_ashr_i32 s1, s0, 31
	s_ashr_i32 s3, s2, 31
	s_xor_b32 s13, s12, 31
	s_lshl_b64 s[10:11], s[0:1], 13
	s_lshl_b64 s[4:5], s[2:3], 1
	v_readlane_b32 s14, v254, 56
	v_readlane_b32 s15, v254, 57
	s_add_u32 s14, s14, s4
	s_addc_u32 s15, s15, s5
	s_lshl_b64 s[0:1], s[0:1], 23
	v_readlane_b32 s16, v254, 58
	v_readlane_b32 s17, v254, 59
	s_add_u32 s3, s16, s0
	s_addc_u32 s16, s17, s1
	s_add_u32 s18, s3, s4
	s_addc_u32 s19, s16, s5
	v_readlane_b32 s4, v254, 60
	v_readlane_b32 s5, v254, 61
	s_add_u32 s4, s4, s0
	s_addc_u32 s5, s5, s1
	s_and_b32 s2, s2, 0xffffff80
	s_ashr_i32 s3, s2, 31
	s_lshl_b64 s[2:3], s[2:3], 1
	s_add_u32 s20, s4, s2
	s_addc_u32 s21, s5, s3
	s_lshl_b32 s4, s6, 7
	s_ashr_i32 s5, s4, 31
	s_lshl_b64 s[4:5], s[4:5], 1
	v_readlane_b32 s16, v255, 8
	v_readlane_b32 s17, v255, 9
	s_add_u32 s33, s16, s4
	s_addc_u32 s86, s17, s5
	s_add_u32 s0, s0, s2
	v_readlane_b32 s24, v254, 6
	s_addc_u32 s1, s1, s3
	v_readlane_b32 s30, v254, 12
	v_readlane_b32 s25, v254, 7
	v_readlane_b32 s26, v254, 8
	v_readlane_b32 s27, v254, 9
	v_readlane_b32 s28, v254, 10
	v_readlane_b32 s29, v254, 11
	v_readlane_b32 s31, v254, 13
	s_add_u32 s22, s30, s0
	s_addc_u32 s23, s31, s1
	v_mov_b32_e32 v225, 0
	s_mov_b64 s[24:25], 0x10000
	s_mov_b64 s[26:27], 0x20000
	s_mov_b64 s[28:29], 0x30000
	s_mov_b64 s[30:31], 0x40000
	s_mov_b64 s[34:35], 0x5820000
	s_mov_b64 s[36:37], 0x5820080
	s_mov_b32 s87, 0x41000000
	v_mov_b32_e32 v1, 0xff800000
	s_mov_b32 s90, 0
	s_branch .LBB0_969
